# adds barrier non-leaders polling the top generation word and h3-before-attention for half the workgroups
# speedup vs baseline: 1.0277x; 1.0061x over previous
; __device__ __forceinline__ unsigned xb_ld(unsigned* p)              { return __hip_atomic_load(p, __ATOMIC_RELAXED, __HIP_MEMORY_SCOPE_AGENT); }
; __device__ __forceinline__ unsigned xb_add(unsigned* p, unsigned v) { return __hip_atomic_fetch_add(p, v, __ATOMIC_RELAXED, __HIP_MEMORY_SCOPE_AGENT); }
; #define XB_SPIN(cond, bar) do { unsigned _sp = 0; while (cond) { __builtin_amdgcn_s_sleep(1); \
;     if ((++_sp & 255u) == 0u) { if (xb_ld(&(bar)[XB_TMO])) break; if (_sp > XB_SPIN_CAP) { atomicAdd(&(bar)[XB_TMO], 1u); break; } } } } while (0)
; __device__ __forceinline__ void xcd_barrier(const XcdBarrier& b) {
;     ...
;         const unsigned old = xb_add(&bar[XB_XSUB(b.x)], 1u);
;         const unsigned gen = old / nloc;
;         if (old + 1u == (gen + 1u) * nloc) {
;             __builtin_amdgcn_fence(__ATOMIC_RELEASE, "agent");
;             asm volatile("s_waitcnt vmcnt(0)" ::: "memory");
;             const unsigned og = xb_add(&bar[XB_TOP], 1u);
;             const unsigned tg = og / nx;
;             if (og + 1u == (tg + 1u) * nx) xb_add(&bar[XB_TOPGEN], 1u);
;             else XB_SPIN(xb_ld(&bar[XB_TOPGEN]) == tg, bar);
;             __builtin_amdgcn_fence(__ATOMIC_ACQUIRE, "agent");
;             xb_add(&bar[XB_XGEN(b.x)], 1u);
;             asm volatile("s_waitcnt vmcnt(0)" ::: "memory");
;         } else {
;             XB_SPIN(xb_ld(&bar[XB_XGEN(b.x)]) == gen, bar);
;             __builtin_amdgcn_fence(__ATOMIC_ACQUIRE, "agent");
;             asm volatile("s_waitcnt vmcnt(0)" ::: "memory");
.LBB0_140:
	s_or_b64 exec, exec, s[10:11]
	v_cvt_f32_u32_e32 v4, v2
	s_waitcnt vmcnt(0)
	v_readfirstlane_b32 s3, v3
	v_sub_u32_e32 v3, 0, v2
	v_rcp_iflag_f32_e32 v4, v4
	v_add_u32_e32 v5, s3, v1
	v_mul_f32_e32 v4, 0x4f7ffffe, v4
	v_cvt_u32_f32_e32 v4, v4
	v_mul_lo_u32 v1, v3, v4
	v_mul_hi_u32 v1, v4, v1
	v_add_u32_e32 v1, v4, v1
	v_mul_hi_u32 v1, v5, v1
	v_mul_lo_u32 v3, v1, v2
	v_sub_u32_e32 v3, v5, v3
	v_add_u32_e32 v4, 1, v1
	v_cmp_ge_u32_e32 vcc, v3, v2
	s_nop 1
	v_cndmask_b32_e32 v1, v1, v4, vcc
	v_sub_u32_e32 v4, v3, v2
	v_cndmask_b32_e32 v3, v3, v4, vcc
	v_add_u32_e32 v4, 1, v1
	v_cmp_ge_u32_e32 vcc, v3, v2
	v_add_u32_e32 v3, 1, v5
	s_nop 0
	v_cndmask_b32_e32 v1, v1, v4, vcc
	v_mul_lo_u32 v4, v2, v1
	v_add_u32_e32 v2, v4, v2
	v_cmp_ne_u32_e32 vcc, v3, v2
	s_and_saveexec_b64 s[8:9], vcc
	s_xor_b64 s[8:9], exec, s[8:9]
	s_cbranch_execz .LBB0_154
	s_waitcnt lgkmcnt(0)
	v_mov_b32_e32 v0, 0x83100
	global_load_dword v0, v0, s[30:31] offset:1024 sc1
	s_add_u32 s14, s30, 0x83500
	s_addc_u32 s15, s31, 0
	s_waitcnt vmcnt(0)
	v_cmp_eq_u32_e32 vcc, v0, v1
	s_and_saveexec_b64 s[10:11], vcc
	s_cbranch_execz .LBB0_153
	s_add_u32 s12, s30, 0x80200
	s_addc_u32 s13, s31, 0
	s_mov_b32 s3, 1
	s_mov_b64 s[16:17], 0
	v_mov_b32_e32 v0, 0
	s_branch .LBB0_144

; __device__ __forceinline__ unsigned xb_ld(unsigned* p)              { return __hip_atomic_load(p, __ATOMIC_RELAXED, __HIP_MEMORY_SCOPE_AGENT); }
; __device__ __forceinline__ unsigned xb_add(unsigned* p, unsigned v) { return __hip_atomic_fetch_add(p, v, __ATOMIC_RELAXED, __HIP_MEMORY_SCOPE_AGENT); }
; #define XB_SPIN(cond, bar) do { unsigned _sp = 0; while (cond) { __builtin_amdgcn_s_sleep(1); \
;     if ((++_sp & 255u) == 0u) { if (xb_ld(&(bar)[XB_TMO])) break; if (_sp > XB_SPIN_CAP) { atomicAdd(&(bar)[XB_TMO], 1u); break; } } } } while (0)
; __device__ __forceinline__ void xcd_barrier(const XcdBarrier& b) {
;     ...
;         const unsigned old = xb_add(&bar[XB_XSUB(b.x)], 1u);
;         const unsigned gen = old / nloc;
;         if (old + 1u == (gen + 1u) * nloc) {
;             __builtin_amdgcn_fence(__ATOMIC_RELEASE, "agent");
;             asm volatile("s_waitcnt vmcnt(0)" ::: "memory");
;             const unsigned og = xb_add(&bar[XB_TOP], 1u);
;             const unsigned tg = og / nx;
;             if (og + 1u == (tg + 1u) * nx) xb_add(&bar[XB_TOPGEN], 1u);
;             else XB_SPIN(xb_ld(&bar[XB_TOPGEN]) == tg, bar);
;             __builtin_amdgcn_fence(__ATOMIC_ACQUIRE, "agent");
;             xb_add(&bar[XB_XGEN(b.x)], 1u);
;             asm volatile("s_waitcnt vmcnt(0)" ::: "memory");
;         } else {
;             XB_SPIN(xb_ld(&bar[XB_XGEN(b.x)]) == gen, bar);
;             __builtin_amdgcn_fence(__ATOMIC_ACQUIRE, "agent");
;             asm volatile("s_waitcnt vmcnt(0)" ::: "memory");
.LBB0_669:
	s_or_b64 exec, exec, s[8:9]
	v_cvt_f32_u32_e32 v4, v2
	s_waitcnt vmcnt(0)
	v_readfirstlane_b32 s3, v3
	v_sub_u32_e32 v3, 0, v2
	v_rcp_iflag_f32_e32 v4, v4
	v_add_u32_e32 v5, s3, v1
	v_mul_f32_e32 v4, 0x4f7ffffe, v4
	v_cvt_u32_f32_e32 v4, v4
	v_mul_lo_u32 v1, v3, v4
	v_mul_hi_u32 v1, v4, v1
	v_add_u32_e32 v1, v4, v1
	v_mul_hi_u32 v1, v5, v1
	v_mul_lo_u32 v3, v1, v2
	v_sub_u32_e32 v3, v5, v3
	v_add_u32_e32 v4, 1, v1
	v_cmp_ge_u32_e32 vcc, v3, v2
	s_nop 1
	v_cndmask_b32_e32 v1, v1, v4, vcc
	v_sub_u32_e32 v4, v3, v2
	v_cndmask_b32_e32 v3, v3, v4, vcc
	v_add_u32_e32 v4, 1, v1
	v_cmp_ge_u32_e32 vcc, v3, v2
	v_add_u32_e32 v3, 1, v5
	s_nop 0
	v_cndmask_b32_e32 v1, v1, v4, vcc
	v_mul_lo_u32 v4, v2, v1
	v_add_u32_e32 v2, v4, v2
	v_cmp_ne_u32_e32 vcc, v3, v2
	s_and_saveexec_b64 s[6:7], vcc
	s_xor_b64 s[6:7], exec, s[6:7]
	s_cbranch_execz .LBB0_683
	s_waitcnt lgkmcnt(0)
	v_mov_b32_e32 v0, 0x83100
	global_load_dword v0, v0, s[30:31] offset:1024 sc1
	s_add_u32 s12, s30, 0x83500
	s_addc_u32 s13, s31, 0
	s_waitcnt vmcnt(0)
	v_cmp_eq_u32_e32 vcc, v0, v1
	s_and_saveexec_b64 s[8:9], vcc
	s_cbranch_execz .LBB0_682
	s_add_u32 s10, s30, 0x80200
	s_addc_u32 s11, s31, 0
	s_mov_b32 s3, 1
	s_mov_b64 s[14:15], 0
	v_mov_b32_e32 v0, 0
	s_branch .LBB0_673

; #define PHASE(k, ...) if (IN(k)) { { __VA_ARGS__ } if (DUPON(k)) { __VA_ARGS__ } SEAM(k); }
; __global__ void __launch_bounds__(NTHR) mk_fwd(Args a) {
;     ...
;     PHASE(7,  const bf16_t* Q = WSB(SL(3)); const bf16_t* K = (const bf16_t*)((unsigned char*)a.out + 64 * MiB); const bf16_t* Vt = WSB(SL(8)); bf16_t* O = (bf16_t*)a.out;
;                  float mfix; { const int ln = threadIdx.x & 63; float gqm = fmaxf(fabsf(a.in[11][ln]), fabsf(a.in[11][64 + (ln & 31)])), gkm = fmaxf(fabsf(a.in[12][ln]), fabsf(a.in[12][64 + (ln & 31)]));
;                      for (int o = 1; o < 64; o <<= 1) { gqm = fmaxf(gqm, __shfl_xor(gqm, o)); gkm = fmaxf(gkm, __shfl_xor(gkm, o)); }
;                      mfix = 14.135f * 1.02f * gqm * gkm; }
;                  const bool fix = mfix <= 40.f;
;                  for (int rep = 0; rep < (DUPON(19) ? 2 : 1); ++rep) {
.LBB0_704:
	s_cmp_lt_i32 s84, 8
	s_cselect_b64 s[0:1], -1, 0
	s_cmp_gt_i32 s85, 7
	s_cselect_b64 s[4:5], -1, 0
	s_and_b64 s[0:1], s[0:1], s[4:5]
	s_andn2_b64 vcc, exec, s[0:1]
	s_cbranch_vccnz .LBB0_893
	s_mov_b32 s98, 0
	s_and_b32 s99, s2, 8
	s_cbranch_scc0 .Lp7_setup
	s_mov_b32 s98, 1
	v_writelane_b32 v255, s74, 9
	v_writelane_b32 v255, s75, 10
	v_writelane_b32 v255, s76, 11
	v_writelane_b32 v255, s77, 12
.Lp7_setup:
	v_and_b32_e32 v195, 31, v254
	s_waitcnt vmcnt(0)
	v_and_b32_e32 v0, 63, v254
	s_waitcnt lgkmcnt(0)
	v_lshlrev_b32_e32 v1, 2, v195
	v_lshlrev_b32_e32 v0, 2, v0
	global_load_dword v2, v1, s[74:75] offset:256
	global_load_dword v3, v0, s[74:75]
	global_load_dword v4, v1, s[76:77] offset:256
	global_load_dword v5, v0, s[76:77]
	v_mbcnt_lo_u32_b32 v0, -1, 0
	v_lshlrev_b32_e32 v16, 3, v254
	v_mbcnt_hi_u32_b32 v0, -1, v0
	v_and_b32_e32 v10, 56, v16
	v_and_b32_e32 v201, 64, v0
	v_add_u32_e32 v6, 0x200, v254
	v_xor_b32_e32 v17, 1, v0
	v_lshlrev_b32_e32 v158, 1, v10
	v_add_u32_e32 v10, 64, v201
	v_mul_u32_u24_e32 v8, 0x1556, v254
	v_mov_b32_e32 v9, 12
	s_mov_b32 s4, 0x7060302
	v_mul_u32_u24_e32 v12, 0x1556, v6
	v_cmp_lt_i32_e32 vcc, v17, v10
	v_mul_lo_u16_sdwa v11, v8, v9 dst_sel:DWORD dst_unused:UNUSED_PAD src0_sel:WORD_1 src1_sel:DWORD
	v_perm_b32 v8, v12, v8, s4
	v_mul_lo_u16_sdwa v9, v12, v9 dst_sel:DWORD dst_unused:UNUSED_PAD src0_sel:WORD_1 src1_sel:DWORD
	v_cndmask_b32_e32 v12, v0, v17, vcc
	v_lshlrev_b32_e32 v12, 2, v12
	v_lshrrev_b32_e32 v7, 3, v254
	v_xor_b32_e32 v18, 2, v0
	v_bfe_u32 v1, v254, 5, 1
	s_movk_i32 s6, 0xd0
	v_mul_u32_u24_e32 v13, 0x88, v7
	v_xor_b32_e32 v19, 4, v0
	v_cmp_lt_i32_e32 vcc, v18, v10
	v_lshlrev_b32_e32 v199, 3, v1
	v_mad_u32_u24 v14, v195, s6, 0
	v_lshlrev_b32_e32 v156, 4, v1
	v_mul_i32_i24_e32 v15, 0xffffffb8, v195
	v_xor_b32_e32 v20, 8, v0
	v_add3_u32 v189, 0, v13, v158
	v_cndmask_b32_e32 v13, v0, v18, vcc
	v_cmp_lt_i32_e32 vcc, v19, v10
	v_xor_b32_e32 v21, 16, v0
	v_add_u32_e32 v188, v14, v156
	v_add3_u32 v198, v14, v15, v199
	v_cndmask_b32_e32 v14, v0, v19, vcc
	v_cmp_lt_i32_e32 vcc, v20, v10
	v_xor_b32_e32 v22, 32, v0
	v_sub_u16_e32 v9, v6, v9
	v_cndmask_b32_e32 v15, v0, v20, vcc
	v_cmp_lt_i32_e32 vcc, v21, v10
	v_lshlrev_b32_e32 v190, 4, v9
	v_lshlrev_b32_e32 v9, 2, v15
	v_cndmask_b32_e32 v17, v0, v21, vcc
	v_cmp_lt_i32_e32 vcc, v22, v10
	v_lshlrev_b32_e32 v10, 2, v13
	v_lshlrev_b32_e32 v186, 2, v17
	v_cndmask_b32_e32 v0, v0, v22, vcc
	v_lshlrev_b32_e32 v187, 2, v0
	s_add_u32 s49, s50, 0x4000000
	s_addc_u32 s54, s51, 0
	s_add_u32 s55, s30, 0x6000000
	s_addc_u32 s56, s31, 0
	s_add_u32 s59, s30, 0x10000000
	s_addc_u32 s60, s31, 0
	s_mov_b32 s3, 0x42200000
	s_cmpk_lt_i32 s2, 0x200
	s_cselect_b64 s[6:7], -1, 0
	s_and_b32 s42, s2, 3
	s_xor_b32 s43, s42, 7
	s_mov_b32 s5, 0xd00068
	v_pk_mul_lo_u16 v8, v8, s5
	v_mov_b32_e32 v157, 0
	v_sub_u16_e32 v11, v254, v11
	v_lshlrev_b16_e32 v11, 3, v11
	s_movk_i32 s0, 0x100
	v_lshlrev_b32_e32 v192, 1, v11
	v_lshrrev_b32_e32 v191, 16, v8
	v_mov_b32_e32 v159, v157
	v_cmp_gt_u32_e64 s[0:1], s0, v254
	v_lshlrev_b32_e32 v206, 3, v6
	v_lshlrev_b32_e32 v207, 15, v7
	v_add_u32_e32 v196, 0, v191
	v_lshlrev_b32_e32 v194, 2, v1
	s_waitcnt vmcnt(3)
	v_max_f32_e64 v2, |v2|, |v2|
	s_waitcnt vmcnt(2)
	v_max_f32_e64 v3, |v3|, |v3|
	s_waitcnt vmcnt(1)
	v_max_f32_e64 v4, |v4|, |v4|
	s_waitcnt vmcnt(0)
	v_max_f32_e64 v5, |v5|, |v5|
	v_max_f32_e32 v2, v3, v2
	v_max_f32_e32 v3, v5, v4
	ds_bpermute_b32 v4, v12, v2
	ds_bpermute_b32 v5, v12, v3
	v_lshlrev_b32_e32 v12, 2, v14
	s_waitcnt lgkmcnt(1)
	v_max_f32_e32 v4, v4, v4
	s_waitcnt lgkmcnt(0)
	v_max_f32_e32 v5, v5, v5
	v_max_f32_e32 v2, v2, v4
	v_max_f32_e32 v3, v3, v5
	ds_bpermute_b32 v4, v10, v2
	ds_bpermute_b32 v5, v10, v3
	v_and_b32_e32 v10, 0xfff8, v8
	v_lshlrev_b32_e32 v193, 1, v10
	v_add3_u32 v197, 0, v193, v192
	s_waitcnt lgkmcnt(1)
	v_max_f32_e32 v4, v4, v4
	s_waitcnt lgkmcnt(0)
	v_max_f32_e32 v5, v5, v5
	v_max_f32_e32 v2, v2, v4
	v_max_f32_e32 v3, v3, v5
	ds_bpermute_b32 v4, v12, v2
	ds_bpermute_b32 v5, v12, v3
	s_waitcnt lgkmcnt(1)
	v_max_f32_e32 v4, v4, v4
	s_waitcnt lgkmcnt(0)
	v_max_f32_e32 v5, v5, v5
	v_max_f32_e32 v2, v2, v4
	v_max_f32_e32 v3, v3, v5
	ds_bpermute_b32 v4, v9, v2
	ds_bpermute_b32 v5, v9, v3
	s_waitcnt lgkmcnt(1)
	v_max_f32_e32 v0, v4, v4
	s_waitcnt lgkmcnt(0)
	v_max_f32_e32 v4, v5, v5
	v_max_f32_e32 v0, v2, v0
	v_max_f32_e32 v2, v3, v4
	ds_bpermute_b32 v3, v186, v0
	ds_bpermute_b32 v4, v186, v2
	s_waitcnt lgkmcnt(1)
	v_max_f32_e32 v3, v3, v3
	s_waitcnt lgkmcnt(0)
	v_max_f32_e32 v4, v4, v4
	v_max_f32_e32 v0, v0, v3
	v_max_f32_e32 v2, v2, v4
	ds_bpermute_b32 v3, v187, v0
	ds_bpermute_b32 v4, v187, v2
	s_waitcnt lgkmcnt(1)
	v_max_f32_e32 v3, v3, v3
	s_waitcnt lgkmcnt(0)
	v_max_f32_e32 v4, v4, v4
	v_max_f32_e32 v0, v0, v3
	v_max_f32_e32 v2, v2, v4
	v_mul_f32_e32 v0, 0x4166aee6, v0
	v_mul_f32_e32 v0, v2, v0
	v_cmp_ge_f32_e32 vcc, s3, v0
	s_ashr_i32 s3, s2, 2
	s_mul_i32 s58, s3, 0xc0000
	s_mul_hi_i32 s57, s3, 0xc0000
	s_add_u32 s4, s55, s58
	s_addc_u32 s5, s56, s57
	s_ashr_i32 s10, s2, 5
	s_and_b32 s3, s3, 7
	s_ashr_i32 s11, s10, 31
	s_lshl_b64 s[8:9], s[10:11], 13
	v_lshl_add_u64 v[154:155], s[4:5], 0, v[156:157]
	s_lshl_b32 s4, s3, 22
	s_add_u32 s4, s59, s4
	s_addc_u32 s5, s60, 0
	s_add_u32 s4, s4, s8
	s_addc_u32 s5, s5, s9
	s_add_u32 s12, s49, s58
	s_addc_u32 s13, s54, s57
	s_lshl_b32 s48, s10, 12
	s_lshl_b32 s3, s3, 7
	v_lshlrev_b32_e32 v2, 4, v6
	v_mov_b32_e32 v3, v157
	s_add_u32 s10, s50, s3
	v_lshl_add_u64 v[148:149], s[12:13], 0, v[2:3]
	v_lshlrev_b32_e32 v2, 16, v7
	s_addc_u32 s11, s51, 0
	v_lshlrev_b32_e32 v156, 4, v254
	v_lshl_add_u64 v[2:3], s[4:5], 0, v[2:3]
	s_cmpk_lg_i32 s86, 0x100
	v_lshl_add_u64 v[152:153], s[12:13], 0, v[156:157]
	v_lshl_add_u64 v[150:151], v[2:3], 0, v[158:159]
	s_cselect_b64 s[12:13], -1, 0
	s_mov_b64 s[4:5], 0
	s_cmp_eq_u32 s98, 1
	s_cbranch_scc0 .Lp7_attn
	s_mov_b64 s[0:1], exec
	s_branch .Lp7_h3
; #define LAS __attribute__((address_space(3)))
; __device__ __forceinline__ void attn_unit64(const bf16_t* Q, const bf16_t* K, const bf16_t* Vt, bf16_t* O, int bh, int qb8, float mfix, LAS unsigned char* lds) {
;     ...
;     const bf16_t* Qh = Q + (size_t)bh * SEQ * 96; const bf16_t* Kh = K + (size_t)bh * SEQ * 96; const bf16_t* Vh = Vt + (size_t)(bh & 7) * 64 * T + (size_t)(bh >> 3) * SEQ;
;     const int q0 = qb8 * 512, qw = q0 + wid * 64, NTL = 8 * (qb8 + 1), tmaxw = 8 * qb8 + wid;
;     LAS bf16x8* Qs = (LAS bf16x8*)(lds + 2 * 64 * 104 * 2 + 2 * 64 * 68 * 2) + tid;
; #pragma unroll
;     for (int d0 = 0; d0 < 6; ++d0) { Qs[512 * d0] = __builtin_nontemporal_load((const bf16x8*)(Qh + (size_t)(qw + r) * 96 + 16 * d0 + 8 * hh)); Qs[512 * (6 + d0)] = __builtin_nontemporal_load((const bf16x8*)(Qh + (size_t)(qw + 32 + r) * 96 + 16 * d0 + 8 * hh)); }
;     f32x16 oA0, oA1, oB0, oB1;
; #pragma unroll
;     for (int i = 0; i < 16; ++i) { oA0[i] = 0.f; oA1[i] = 0.f; oB0[i] = 0.f; oB1[i] = 0.f; }
;     float lA = 0.f, lB = 0.f;
;     const int c2 = 512 + tid, kr1 = tid / 12, kc1 = tid % 12, kr2 = c2 / 12, kc2 = c2 % 12, vr = tid >> 3, vc = tid & 7;
; __global__ void __launch_bounds__(NTHR) mk_fwd(Args a) {
;     ...
;                  const bool fix = mfix <= 40.f;
;                  for (int rep = 0; rep < (DUPON(19) ? 2 : 1); ++rep) {
;                  if (fix) { if (G == 256) { const int bh = bid >> 2, s = bid & 3; attn_unit64(Q, K, Vt, O, bh, 7 - s, mfix, lds); attn_unit64(Q, K, Vt, O, bh, s, mfix, lds); }
;                             else { for (int j = bid; j < 512; j += G) attn_unit64(Q, K, Vt, O, j >> 3, 7 - (j & 7), mfix, lds); } }
.Lp7_attn:
	s_and_saveexec_b64 s[14:15], vcc
	s_xor_b64 s[14:15], exec, s[14:15]
	s_cbranch_execz .LBB0_731
	v_lshl_add_u32 v200, v254, 4, 0
	v_xor_b32_e32 v0, 0x80000000, v0
	v_add_u32_e32 v201, 0xac00, v200
	v_add_u32_e32 v202, 0x1ac00, v200
	v_add_u32_e32 v203, 0x1cc00, v200
	v_add_u32_e32 v204, 0x1ec00, v200
	v_add_u32_e32 v205, 0x20c00, v200
	v_mov_b32_e32 v1, v0
	v_mov_b32_e32 v2, v0
	v_mov_b32_e32 v3, v0
	v_mov_b32_e32 v4, v0
	v_mov_b32_e32 v5, v0
	v_mov_b32_e32 v6, v0
	v_mov_b32_e32 v7, v0
	v_mov_b32_e32 v8, v0
	v_mov_b32_e32 v9, v0
	v_mov_b32_e32 v10, v0
	v_mov_b32_e32 v11, v0
	v_mov_b32_e32 v12, v0
	v_mov_b32_e32 v13, v0
	v_mov_b32_e32 v14, v0
	v_mov_b32_e32 v15, v0
	s_and_b64 vcc, exec, s[12:13]
	s_cbranch_vccz .LBB0_786
	s_mov_b64 s[16:17], 0
	s_and_b64 vcc, exec, s[6:7]
	s_cbranch_vccz .LBB0_787
	v_mov_b32_e32 v112, 0
	v_mov_b32_e32 v157, v112
	v_lshl_add_u64 v[18:19], s[50:51], 0, v[156:157]
	s_mov_b64 s[4:5], 0x4003000
	v_lshl_add_u64 v[128:129], v[18:19], 0, s[4:5]
	v_and_b32_e32 v18, 7, v254
	v_lshlrev_b32_e32 v17, 13, v254
	v_lshlrev_b32_e32 v18, 4, v18
	s_mov_b32 s4, 0x7f0000
	v_and_or_b32 v18, v17, s4, v18
	v_mov_b32_e32 v19, v112
	v_lshl_add_u64 v[18:19], s[30:31], 0, v[18:19]
	s_mov_b64 s[4:5], 0x10000080
	v_lshlrev_b32_e32 v132, 1, v199
	s_xor_b32 s3, s2, 7
	v_lshl_add_u64 v[130:131], v[18:19], 0, s[4:5]
	s_movk_i32 s28, 0xc0
	v_mov_b32_e32 v134, v132
	v_mov_b32_e32 v135, v112
	v_lshlrev_b32_e32 v157, 1, v16
	s_mov_b32 s19, 0
	v_lshlrev_b32_e32 v136, 1, v207
	v_mov_b32_e32 v137, v112
	v_mov_b32_e32 v159, v112
	v_add_u32_e32 v207, v196, v190
	v_add_u32_e32 v208, 0x6800, v189
	v_mov_b32_e32 v209, 0xc0000
	s_mov_b64 s[20:21], 0x3000
	s_mov_b64 s[22:23], 0x80
	s_mov_b64 s[24:25], 0x10000
	s_mov_b32 s29, 0x10000
	v_lshlrev_b32_e32 v206, 1, v206
	v_mov_b32_e32 v210, 0xf149f2ca
	s_mov_b32 s61, s2
	s_branch .LBB0_710

; __device__ __forceinline__ void h3_unit(int j, const bf16_t* qe, const bf16_t* intra, const bf16_t* Ub, const bf16_t* hg, const float* gn, bf16_t* out) {
;     const int tid = threadIdx.x, lane = tid & 63, wid = __builtin_amdgcn_readfirstlane(tid >> 6), l15 = lane & 15, l4 = lane >> 4;
;     const int b = j >> 6, c = j & 63, t0 = b * SEQ + c * 64;
; #pragma unroll 1
;     for (int cc = 0; cc < 2; ++cc) {
;         const int combo = 2 * wid + cc, head = combo >> 2, tb = combo & 3, u = (b * 4 + head) * 64 + c;
;         const size_t rbase = (size_t)(t0 + 16 * tb + l15) * 512 + head * 128;
;         bf16x8 x[4];
; #pragma unroll
;         for (int ks = 0; ks < 4; ++ks) x[ks] = __builtin_nontemporal_load((const bf16x8*)(qe + rbase + 8 * l4 + 32 * ks));
;         u32x2 iv[8], gv[8];
; #pragma unroll
;         for (int vb = 0; vb < 8; ++vb) { iv[vb] = __builtin_nontemporal_load((const u32x2*)(intra + rbase + 16 * vb + 4 * l4)); gv[vb] = __builtin_nontemporal_load((const u32x2*)(hg + rbase + 16 * vb + 4 * l4)); }
;         const bf16_t* ub = Ub + (size_t)u * 16384 + l15 * 128 + 8 * l4;
; __global__ void __launch_bounds__(NTHR) mk_fwd(Args a) {
;     ...
;                  for (int j = bid; j < 512; j += G) h3_unit(j, WSB(SL(6)), WSB(SL(7)), WSB(SL(14)), WSB(SL(9)), a.in[14], (bf16_t*)a.out);
.LBB0_833:
	s_cmp_eq_u32 s98, 2
	s_cbranch_scc1 .LBB0_838
	s_and_b64 vcc, exec, s[6:7]
	s_cbranch_vccz .LBB0_838
.Lp7_h3:
	v_bfe_u32 v2, v254, 4, 2
	v_mov_b32_e32 v1, 0
	v_lshlrev_b32_e32 v0, 3, v2
	v_lshlrev_b32_e32 v2, 4, v2
	v_mov_b32_e32 v3, v1
	v_lshl_add_u64 v[4:5], s[30:31], 0, v[2:3]
	s_mov_b64 s[4:5], 0xc000000
	v_lshl_add_u64 v[64:65], v[4:5], 0, s[4:5]
	v_lshl_add_u64 v[4:5], s[30:31], 0, v[0:1]
	s_mov_b64 s[4:5], 0xe000000
	v_and_b32_e32 v184, 15, v254
	v_lshl_add_u64 v[66:67], v[4:5], 0, s[4:5]
	s_mov_b64 s[4:5], 0x12000000
	v_lshl_add_u64 v[68:69], v[4:5], 0, s[4:5]
	v_lshlrev_b32_e32 v4, 8, v184
	v_mov_b32_e32 v5, v1
	v_lshl_add_u64 v[4:5], s[30:31], 0, v[4:5]
	v_lshl_add_u64 v[4:5], v[4:5], 0, v[2:3]
	s_mov_b64 s[4:5], 0x1c000000
	v_lshl_add_u64 v[70:71], v[4:5], 0, s[4:5]
	v_lshl_add_u64 v[72:73], s[80:81], 0, v[2:3]
	v_lshl_add_u64 v[74:75], s[50:51], 0, v[0:1]
	s_mov_b64 s[4:5], 0x1000
	s_mov_b64 s[6:7], 0x1040
	s_mov_b64 s[8:9], 0x1080
	s_mov_b64 s[10:11], 0x10c0
	s_mov_b64 s[12:13], 0x2000
	s_mov_b64 s[14:15], 0x2040
	s_mov_b64 s[16:17], 0x2080
	s_mov_b64 s[18:19], 0x20c0
	s_mov_b64 s[20:21], 0x3000
	s_mov_b64 s[22:23], 0x3040
	s_mov_b64 s[24:25], 0x3080
	s_mov_b64 s[26:27], 0x30c0
	s_mov_b64 s[36:37], 0x4000
	s_mov_b64 s[38:39], 0x4040
	s_mov_b64 s[42:43], 0x4080
	s_mov_b64 s[48:49], 0x40c0
	s_mov_b64 s[54:55], 0x5000
	s_mov_b64 s[56:57], 0x5040
	s_mov_b64 s[58:59], 0x5080
	s_mov_b64 s[60:61], 0x50c0
	s_mov_b64 s[62:63], 0x6000
	s_mov_b64 s[64:65], 0x6040
	s_mov_b64 s[66:67], 0x6080
	s_mov_b64 s[68:69], 0x60c0
	s_mov_b64 s[70:71], 0x7000
	s_mov_b64 s[72:73], 0x7040
	s_mov_b64 s[74:75], 0x7080
	s_mov_b64 s[76:77], 0x70c0
	v_mov_b32_e32 v185, 0x358637bd
	s_mov_b32 s3, 0x800000
	s_mov_b32 s28, s2

; __device__ __forceinline__ unsigned xb_ld(unsigned* p)              { return __hip_atomic_load(p, __ATOMIC_RELAXED, __HIP_MEMORY_SCOPE_AGENT); }
; __device__ __forceinline__ void xcd_barrier_complete(unsigned* bar, unsigned x, unsigned& nloc, unsigned& nx) {
;     const unsigned G = gridDim.x * gridDim.y * gridDim.z;
;     unsigned sum, cnt, mine, sp = 0u;
;     for (;;) {
;         sum = 0u; cnt = 0u; mine = 0u;
; #pragma unroll
;         for (unsigned j = 0; j < 16; ++j) { const unsigned c = xb_ld(&bar[XB_XCNT(j)]); sum += c; cnt += (c > 0u) ? 1u : 0u; mine = (j == x) ? c : mine; }
;         if (sum == G) break;
; __device__ __forceinline__ void xcd_barrier(const XcdBarrier& b) {
;     asm volatile("s_waitcnt vmcnt(0)" ::: "memory");
;     __syncthreads();
;     if (threadIdx.x == 0) {
;         unsigned* bar = b.bar;
;         __builtin_amdgcn_s_waitcnt(0);
;         unsigned nloc = b.st[0], nx = b.st[1];
;         if (nloc == 0u) { xcd_barrier_complete(bar, b.x, nloc, nx); b.st[0] = nloc; b.st[1] = nx; }
.LBB0_838:
	s_or_b64 exec, exec, s[0:1]
	s_cmp_eq_u32 s98, 1
	s_cbranch_scc0 .Lp7_done
	s_mov_b32 s98, 2
	v_readlane_b32 s74, v255, 9
	v_readlane_b32 s75, v255, 10
	v_readlane_b32 s76, v255, 11
	v_readlane_b32 s77, v255, 12
	s_branch .Lp7_setup
.Lp7_done:
	s_cmp_gt_i32 s85, 8
	s_cbranch_scc0 .LBB0_893
	s_waitcnt vmcnt(0)
	s_barrier
	s_mov_b64 s[0:1], exec
	v_readlane_b32 s4, v255, 1
	v_readlane_b32 s5, v255, 2
	s_and_b64 s[4:5], s[0:1], s[4:5]
	s_mov_b64 exec, s[4:5]
	s_cbranch_execz .LBB0_892
	s_add_i32 s3, 0, 0x23fc0
	v_mov_b32_e32 v0, s3
	s_waitcnt vmcnt(0) expcnt(0) lgkmcnt(0)
	ds_read_b32 v2, v0
	s_add_i32 s3, 0, 0x23fc4
	v_mov_b32_e32 v0, s3
	ds_read_b32 v0, v0
	s_waitcnt lgkmcnt(1)
	v_cmp_ne_u32_e32 vcc, 0, v2
	s_cbranch_vccnz .LBB0_856
	s_add_u32 s4, s30, 0x80200
	s_addc_u32 s5, s31, 0
	s_add_u32 s6, s30, 0x80400
	s_addc_u32 s7, s31, 0
	s_add_u32 s8, s30, 0x80500
	s_addc_u32 s9, s31, 0
	s_add_u32 s10, s30, 0x80600
	s_addc_u32 s11, s31, 0
	s_add_u32 s12, s30, 0x80700
	s_addc_u32 s13, s31, 0
	s_add_u32 s14, s30, 0x80800
	s_addc_u32 s15, s31, 0
	s_add_u32 s16, s30, 0x80900
	s_addc_u32 s17, s31, 0
	s_add_u32 s18, s30, 0x80a00
	s_addc_u32 s19, s31, 0
	s_add_u32 s20, s30, 0x80b00
	s_addc_u32 s21, s31, 0
	s_add_u32 s22, s30, 0x80c00
	s_addc_u32 s23, s31, 0
	s_add_u32 s24, s30, 0x80d00
	s_addc_u32 s25, s31, 0
	s_add_u32 s26, s30, 0x80e00
	s_addc_u32 s27, s31, 0
	s_add_u32 s36, s30, 0x80f00
	s_addc_u32 s37, s31, 0
	s_add_u32 s38, s30, 0x81000
	s_addc_u32 s39, s31, 0
	s_add_u32 s42, s30, 0x81100
	s_addc_u32 s43, s31, 0
	s_add_u32 s48, s30, 0x81200
	v_readlane_b32 s3, v255, 0
	s_addc_u32 s49, s31, 0
	s_mul_i32 s3, s87, s3
	s_add_u32 s54, s30, 0x81300
	s_mul_i32 s3, s3, s86
	s_addc_u32 s55, s31, 0
	s_mov_b32 s28, 1
	v_mov_b32_e32 v16, 0
	s_branch .LBB0_843

; __device__ __forceinline__ unsigned xb_ld(unsigned* p)              { return __hip_atomic_load(p, __ATOMIC_RELAXED, __HIP_MEMORY_SCOPE_AGENT); }
; __device__ __forceinline__ unsigned xb_add(unsigned* p, unsigned v) { return __hip_atomic_fetch_add(p, v, __ATOMIC_RELAXED, __HIP_MEMORY_SCOPE_AGENT); }
; #define XB_SPIN(cond, bar) do { unsigned _sp = 0; while (cond) { __builtin_amdgcn_s_sleep(1); \
;     if ((++_sp & 255u) == 0u) { if (xb_ld(&(bar)[XB_TMO])) break; if (_sp > XB_SPIN_CAP) { atomicAdd(&(bar)[XB_TMO], 1u); break; } } } } while (0)
; __device__ __forceinline__ void xcd_barrier(const XcdBarrier& b) {
;     ...
;         const unsigned old = xb_add(&bar[XB_XSUB(b.x)], 1u);
;         const unsigned gen = old / nloc;
;         if (old + 1u == (gen + 1u) * nloc) {
;             __builtin_amdgcn_fence(__ATOMIC_RELEASE, "agent");
;             asm volatile("s_waitcnt vmcnt(0)" ::: "memory");
;             const unsigned og = xb_add(&bar[XB_TOP], 1u);
;             const unsigned tg = og / nx;
;             if (og + 1u == (tg + 1u) * nx) xb_add(&bar[XB_TOPGEN], 1u);
;             else XB_SPIN(xb_ld(&bar[XB_TOPGEN]) == tg, bar);
;             __builtin_amdgcn_fence(__ATOMIC_ACQUIRE, "agent");
;             xb_add(&bar[XB_XGEN(b.x)], 1u);
;             asm volatile("s_waitcnt vmcnt(0)" ::: "memory");
;         } else {
;             XB_SPIN(xb_ld(&bar[XB_XGEN(b.x)]) == gen, bar);
;             __builtin_amdgcn_fence(__ATOMIC_ACQUIRE, "agent");
;             asm volatile("s_waitcnt vmcnt(0)" ::: "memory");
.LBB0_1506:
	s_or_b64 exec, exec, s[6:7]
	v_cvt_f32_u32_e32 v4, v2
	s_waitcnt vmcnt(0)
	v_readfirstlane_b32 s4, v3
	v_sub_u32_e32 v3, 0, v2
	v_rcp_iflag_f32_e32 v4, v4
	v_add_u32_e32 v5, s4, v1
	v_mul_f32_e32 v4, 0x4f7ffffe, v4
	v_cvt_u32_f32_e32 v4, v4
	v_mul_lo_u32 v1, v3, v4
	v_mul_hi_u32 v1, v4, v1
	v_add_u32_e32 v1, v4, v1
	v_mul_hi_u32 v1, v5, v1
	v_mul_lo_u32 v3, v1, v2
	v_sub_u32_e32 v3, v5, v3
	v_add_u32_e32 v4, 1, v1
	v_cmp_ge_u32_e32 vcc, v3, v2
	s_nop 1
	v_cndmask_b32_e32 v1, v1, v4, vcc
	v_sub_u32_e32 v4, v3, v2
	v_cndmask_b32_e32 v3, v3, v4, vcc
	v_add_u32_e32 v4, 1, v1
	v_cmp_ge_u32_e32 vcc, v3, v2
	v_add_u32_e32 v3, 1, v5
	s_nop 0
	v_cndmask_b32_e32 v1, v1, v4, vcc
	v_mul_lo_u32 v4, v2, v1
	v_add_u32_e32 v2, v4, v2
	v_cmp_ne_u32_e32 vcc, v3, v2
	s_and_saveexec_b64 s[4:5], vcc
	s_xor_b64 s[4:5], exec, s[4:5]
	s_cbranch_execz .LBB0_1520
	s_waitcnt lgkmcnt(0)
	v_mov_b32_e32 v0, 0x83100
	global_load_dword v0, v0, s[30:31] offset:1024 sc1
	s_add_u32 s10, s30, 0x83500
	s_addc_u32 s11, s31, 0
	s_waitcnt vmcnt(0)
	v_cmp_eq_u32_e32 vcc, v0, v1
	s_and_saveexec_b64 s[6:7], vcc
	s_cbranch_execz .LBB0_1519
	s_add_u32 s8, s30, 0x80200
	s_addc_u32 s9, s31, 0
	s_mov_b32 s22, 1
	s_mov_b64 s[12:13], 0
	v_mov_b32_e32 v0, 0
	s_branch .LBB0_1510
